# grid barrier: last-arriving XCD leader bumps all XCD generation words (one hop less for waiters), on top of packed gelu
# speedup vs baseline: 1.0994x; 1.0012x over previous
; __device__ __forceinline__ unsigned xb_ld(unsigned* p)              { return __hip_atomic_load(p, __ATOMIC_RELAXED, __HIP_MEMORY_SCOPE_AGENT); }
; __device__ __forceinline__ unsigned xb_add(unsigned* p, unsigned v) { return __hip_atomic_fetch_add(p, v, __ATOMIC_RELAXED, __HIP_MEMORY_SCOPE_AGENT); }
; #define XB_SPIN(cond, bar) do { unsigned _sp = 0; while (cond) { __builtin_amdgcn_s_sleep(1); \
;     if ((++_sp & 255u) == 0u) { if (xb_ld(&(bar)[XB_TMO])) break; if (_sp > XB_SPIN_CAP) { atomicAdd(&(bar)[XB_TMO], 1u); break; } } } } while (0)
; __device__ __forceinline__ void xcd_barrier(const XcdBarrier& b) {
;     ...
;         const unsigned old = xb_add(&bar[XB_XSUB(b.x)], 1u);
;         const unsigned gen = old / nloc;
;         if (old + 1u == (gen + 1u) * nloc) {
;             __builtin_amdgcn_fence(__ATOMIC_RELEASE, "agent");
;             asm volatile("s_waitcnt vmcnt(0)" ::: "memory");
;             const unsigned og = xb_add(&bar[XB_TOP], 1u);
;             const unsigned tg = og / nx;
;             asm volatile("buffer_inv sc1" ::: "memory");
;             if (og + 1u == (tg + 1u) * nx) xb_add(&bar[XB_TOPGEN], 1u);
;             else XB_SPIN(xb_ld(&bar[XB_TOPGEN]) == tg, bar);
.LBB0_116:
	s_or_b64 exec, exec, s[8:9]
	v_cvt_f32_u32_e32 v3, v1
	s_waitcnt vmcnt(0)
	v_readfirstlane_b32 s6, v2
	buffer_inv sc1
	s_add_u32 s8, s58, 0xc93b500
	v_rcp_iflag_f32_e32 v3, v3
	v_add_u32_e32 v0, s6, v0
	s_addc_u32 s9, s59, 0
	s_mov_b64 s[10:11], -1
	v_mul_f32_e32 v2, 0x4f7ffffe, v3
	v_cvt_u32_f32_e32 v2, v2
	v_sub_u32_e32 v3, 0, v1
	v_mul_lo_u32 v3, v3, v2
	v_mul_hi_u32 v3, v2, v3
	v_add_u32_e32 v2, v2, v3
	v_mul_hi_u32 v2, v0, v2
	v_mul_lo_u32 v3, v2, v1
	v_sub_u32_e32 v3, v0, v3
	v_add_u32_e32 v4, 1, v2
	v_cmp_ge_u32_e32 vcc, v3, v1
	v_add_u32_e32 v0, 1, v0
	s_nop 0
	v_cndmask_b32_e32 v2, v2, v4, vcc
	v_sub_u32_e32 v4, v3, v1
	v_cndmask_b32_e32 v3, v3, v4, vcc
	v_add_u32_e32 v4, 1, v2
	v_cmp_ge_u32_e32 vcc, v3, v1
	s_nop 1
	v_cndmask_b32_e32 v2, v2, v4, vcc
	v_mul_lo_u32 v3, v1, v2
	v_add_u32_e32 v1, v3, v1
	v_cmp_ne_u32_e32 vcc, v0, v1
	v_mov_b64_e32 v[0:1], s[8:9]
	v_mov_b32_e32 v30, 0
	s_and_saveexec_b64 s[6:7], vcc
	s_cbranch_execz .LBB0_128
	v_mov_b32_e32 v30, 1
	v_mov_b32_e32 v0, 0
	global_load_dword v1, v0, s[8:9] sc1
	s_mov_b64 s[26:27], 0
	s_waitcnt vmcnt(0)
	v_cmp_eq_u32_e32 vcc, v1, v2
	s_and_saveexec_b64 s[14:15], vcc
	s_cbranch_execz .LBB0_127
	s_add_u32 s10, s58, 0xc938200
	s_addc_u32 s11, s59, 0
	s_mov_b32 s12, 1
	s_branch .LBB0_120

; __device__ __forceinline__ unsigned xb_ld(unsigned* p)              { return __hip_atomic_load(p, __ATOMIC_RELAXED, __HIP_MEMORY_SCOPE_AGENT); }
; __device__ __forceinline__ unsigned xb_add(unsigned* p, unsigned v) { return __hip_atomic_fetch_add(p, v, __ATOMIC_RELAXED, __HIP_MEMORY_SCOPE_AGENT); }
; #define XB_SPIN(cond, bar) do { unsigned _sp = 0; while (cond) { __builtin_amdgcn_s_sleep(1); \
;     if ((++_sp & 255u) == 0u) { if (xb_ld(&(bar)[XB_TMO])) break; if (_sp > XB_SPIN_CAP) { atomicAdd(&(bar)[XB_TMO], 1u); break; } } } } while (0)
; __device__ __forceinline__ void xcd_barrier(const XcdBarrier& b) {
;     ...
;             if (og + 1u == (tg + 1u) * nx) xb_add(&bar[XB_TOPGEN], 1u);
;             else XB_SPIN(xb_ld(&bar[XB_TOPGEN]) == tg, bar);
;             xb_add(&bar[XB_XGEN(b.x)], 1u);
;             asm volatile("s_waitcnt vmcnt(0)" ::: "memory");
.LBB0_130:
	s_or_b64 exec, exec, s[6:7]
	v_cmp_eq_u32_e32 vcc, 0, v30
	s_and_saveexec_b64 s[6:7], vcc
	s_cbranch_execz .LBB0_132
	s_mov_b64 exec, 0xffff
	v_mbcnt_lo_u32_b32 v0, -1, 0
	v_lshlrev_b32_e32 v0, 8, v0
	v_mov_b32_e32 v1, 1
	s_add_u32 s8, s58, 0xc93a400
	s_addc_u32 s9, s59, 0
	global_atomic_add v0, v1, s[8:9]
	s_mov_b64 exec, 1

; __device__ __forceinline__ unsigned xb_ld(unsigned* p)              { return __hip_atomic_load(p, __ATOMIC_RELAXED, __HIP_MEMORY_SCOPE_AGENT); }
; __device__ __forceinline__ unsigned xb_add(unsigned* p, unsigned v) { return __hip_atomic_fetch_add(p, v, __ATOMIC_RELAXED, __HIP_MEMORY_SCOPE_AGENT); }
; #define XB_SPIN(cond, bar) do { unsigned _sp = 0; while (cond) { __builtin_amdgcn_s_sleep(1); \
;     if ((++_sp & 255u) == 0u) { if (xb_ld(&(bar)[XB_TMO])) break; if (_sp > XB_SPIN_CAP) { atomicAdd(&(bar)[XB_TMO], 1u); break; } } } } while (0)
; __device__ __forceinline__ void xcd_barrier(const XcdBarrier& b) {
;     ...
;         const unsigned old = xb_add(&bar[XB_XSUB(b.x)], 1u);
;         const unsigned gen = old / nloc;
;         if (old + 1u == (gen + 1u) * nloc) {
;             __builtin_amdgcn_fence(__ATOMIC_RELEASE, "agent");
;             asm volatile("s_waitcnt vmcnt(0)" ::: "memory");
;             const unsigned og = xb_add(&bar[XB_TOP], 1u);
;             const unsigned tg = og / nx;
;             asm volatile("buffer_inv sc1" ::: "memory");
;             if (og + 1u == (tg + 1u) * nx) xb_add(&bar[XB_TOPGEN], 1u);
;             else XB_SPIN(xb_ld(&bar[XB_TOPGEN]) == tg, bar);
.LBB0_183:
	s_or_b64 exec, exec, s[10:11]
	v_cvt_f32_u32_e32 v3, v1
	s_waitcnt vmcnt(0)
	v_readfirstlane_b32 s8, v2
	buffer_inv sc1
	s_add_u32 s10, s58, 0xc93b500
	v_rcp_iflag_f32_e32 v3, v3
	v_add_u32_e32 v0, s8, v0
	s_addc_u32 s11, s59, 0
	s_mov_b64 s[14:15], -1
	v_mul_f32_e32 v2, 0x4f7ffffe, v3
	v_cvt_u32_f32_e32 v2, v2
	v_sub_u32_e32 v3, 0, v1
	v_mul_lo_u32 v3, v3, v2
	v_mul_hi_u32 v3, v2, v3
	v_add_u32_e32 v2, v2, v3
	v_mul_hi_u32 v2, v0, v2
	v_mul_lo_u32 v3, v2, v1
	v_sub_u32_e32 v3, v0, v3
	v_add_u32_e32 v4, 1, v2
	v_cmp_ge_u32_e32 vcc, v3, v1
	v_add_u32_e32 v0, 1, v0
	s_nop 0
	v_cndmask_b32_e32 v2, v2, v4, vcc
	v_sub_u32_e32 v4, v3, v1
	v_cndmask_b32_e32 v3, v3, v4, vcc
	v_add_u32_e32 v4, 1, v2
	v_cmp_ge_u32_e32 vcc, v3, v1
	s_nop 1
	v_cndmask_b32_e32 v2, v2, v4, vcc
	v_mul_lo_u32 v3, v1, v2
	v_add_u32_e32 v1, v3, v1
	v_cmp_ne_u32_e32 vcc, v0, v1
	v_mov_b64_e32 v[0:1], s[10:11]
	v_mov_b32_e32 v30, 0
	s_and_saveexec_b64 s[8:9], vcc
	s_cbranch_execz .LBB0_195
	v_mov_b32_e32 v30, 1
	v_mov_b32_e32 v0, 0
	global_load_dword v1, v0, s[10:11] sc1
	s_mov_b64 s[46:47], 0
	s_waitcnt vmcnt(0)
	v_cmp_eq_u32_e32 vcc, v1, v2
	s_and_saveexec_b64 s[30:31], vcc
	s_cbranch_execz .LBB0_194
	s_add_u32 s14, s58, 0xc938200
	s_addc_u32 s15, s59, 0
	s_mov_b32 s12, 1
	s_branch .LBB0_187

; __device__ __forceinline__ unsigned xb_ld(unsigned* p)              { return __hip_atomic_load(p, __ATOMIC_RELAXED, __HIP_MEMORY_SCOPE_AGENT); }
; __device__ __forceinline__ unsigned xb_add(unsigned* p, unsigned v) { return __hip_atomic_fetch_add(p, v, __ATOMIC_RELAXED, __HIP_MEMORY_SCOPE_AGENT); }
; #define XB_SPIN(cond, bar) do { unsigned _sp = 0; while (cond) { __builtin_amdgcn_s_sleep(1); \
;     if ((++_sp & 255u) == 0u) { if (xb_ld(&(bar)[XB_TMO])) break; if (_sp > XB_SPIN_CAP) { atomicAdd(&(bar)[XB_TMO], 1u); break; } } } } while (0)
; __device__ __forceinline__ void xcd_barrier(const XcdBarrier& b) {
;     ...
;             if (og + 1u == (tg + 1u) * nx) xb_add(&bar[XB_TOPGEN], 1u);
;             else XB_SPIN(xb_ld(&bar[XB_TOPGEN]) == tg, bar);
;             xb_add(&bar[XB_XGEN(b.x)], 1u);
;             asm volatile("s_waitcnt vmcnt(0)" ::: "memory");
.LBB0_197:
	s_or_b64 exec, exec, s[8:9]
	v_cmp_eq_u32_e32 vcc, 0, v30
	s_and_saveexec_b64 s[8:9], vcc
	s_cbranch_execz .LBB0_199
	s_mov_b64 exec, 0xffff
	v_mbcnt_lo_u32_b32 v0, -1, 0
	v_lshlrev_b32_e32 v0, 8, v0
	v_mov_b32_e32 v1, 1
	s_add_u32 s10, s58, 0xc93a400
	s_addc_u32 s11, s59, 0
	global_atomic_add v0, v1, s[10:11]
	s_mov_b64 exec, 1

; __device__ __forceinline__ unsigned xb_ld(unsigned* p)              { return __hip_atomic_load(p, __ATOMIC_RELAXED, __HIP_MEMORY_SCOPE_AGENT); }
; __device__ __forceinline__ unsigned xb_add(unsigned* p, unsigned v) { return __hip_atomic_fetch_add(p, v, __ATOMIC_RELAXED, __HIP_MEMORY_SCOPE_AGENT); }
; #define XB_SPIN(cond, bar) do { unsigned _sp = 0; while (cond) { __builtin_amdgcn_s_sleep(1); \
;     if ((++_sp & 255u) == 0u) { if (xb_ld(&(bar)[XB_TMO])) break; if (_sp > XB_SPIN_CAP) { atomicAdd(&(bar)[XB_TMO], 1u); break; } } } } while (0)
; __device__ __forceinline__ void xcd_barrier(const XcdBarrier& b) {
;     ...
;         const unsigned old = xb_add(&bar[XB_XSUB(b.x)], 1u);
;         const unsigned gen = old / nloc;
;         if (old + 1u == (gen + 1u) * nloc) {
;             __builtin_amdgcn_fence(__ATOMIC_RELEASE, "agent");
;             asm volatile("s_waitcnt vmcnt(0)" ::: "memory");
;             const unsigned og = xb_add(&bar[XB_TOP], 1u);
;             const unsigned tg = og / nx;
;             asm volatile("buffer_inv sc1" ::: "memory");
;             if (og + 1u == (tg + 1u) * nx) xb_add(&bar[XB_TOPGEN], 1u);
;             else XB_SPIN(xb_ld(&bar[XB_TOPGEN]) == tg, bar);
.LBB0_426:
	s_or_b64 exec, exec, s[8:9]
	v_cvt_f32_u32_e32 v3, v1
	s_waitcnt vmcnt(0)
	v_readfirstlane_b32 s6, v2
	buffer_inv sc1
	s_add_u32 s8, s58, 0xc93b500
	v_rcp_iflag_f32_e32 v3, v3
	v_add_u32_e32 v0, s6, v0
	s_addc_u32 s9, s59, 0
	s_mov_b64 s[10:11], -1
	v_mul_f32_e32 v2, 0x4f7ffffe, v3
	v_cvt_u32_f32_e32 v2, v2
	v_sub_u32_e32 v3, 0, v1
	v_mul_lo_u32 v3, v3, v2
	v_mul_hi_u32 v3, v2, v3
	v_add_u32_e32 v2, v2, v3
	v_mul_hi_u32 v2, v0, v2
	v_mul_lo_u32 v3, v2, v1
	v_sub_u32_e32 v3, v0, v3
	v_add_u32_e32 v4, 1, v2
	v_cmp_ge_u32_e32 vcc, v3, v1
	v_add_u32_e32 v0, 1, v0
	s_nop 0
	v_cndmask_b32_e32 v2, v2, v4, vcc
	v_sub_u32_e32 v4, v3, v1
	v_cndmask_b32_e32 v3, v3, v4, vcc
	v_add_u32_e32 v4, 1, v2
	v_cmp_ge_u32_e32 vcc, v3, v1
	s_nop 1
	v_cndmask_b32_e32 v2, v2, v4, vcc
	v_mul_lo_u32 v3, v1, v2
	v_add_u32_e32 v1, v3, v1
	v_cmp_ne_u32_e32 vcc, v0, v1
	v_mov_b64_e32 v[0:1], s[8:9]
	v_mov_b32_e32 v30, 0
	s_and_saveexec_b64 s[6:7], vcc
	s_cbranch_execz .LBB0_438
	v_mov_b32_e32 v30, 1
	v_mov_b32_e32 v0, 0
	global_load_dword v1, v0, s[8:9] sc1
	s_mov_b64 s[52:53], 0
	s_waitcnt vmcnt(0)
	v_cmp_eq_u32_e32 vcc, v1, v2
	s_and_saveexec_b64 s[18:19], vcc
	s_cbranch_execz .LBB0_437
	s_add_u32 s10, s58, 0xc938200
	s_addc_u32 s11, s59, 0
	s_mov_b32 s12, 1
	s_branch .LBB0_430

; __device__ __forceinline__ unsigned xb_ld(unsigned* p)              { return __hip_atomic_load(p, __ATOMIC_RELAXED, __HIP_MEMORY_SCOPE_AGENT); }
; __device__ __forceinline__ unsigned xb_add(unsigned* p, unsigned v) { return __hip_atomic_fetch_add(p, v, __ATOMIC_RELAXED, __HIP_MEMORY_SCOPE_AGENT); }
; #define XB_SPIN(cond, bar) do { unsigned _sp = 0; while (cond) { __builtin_amdgcn_s_sleep(1); \
;     if ((++_sp & 255u) == 0u) { if (xb_ld(&(bar)[XB_TMO])) break; if (_sp > XB_SPIN_CAP) { atomicAdd(&(bar)[XB_TMO], 1u); break; } } } } while (0)
; __device__ __forceinline__ void xcd_barrier(const XcdBarrier& b) {
;     ...
;         const unsigned old = xb_add(&bar[XB_XSUB(b.x)], 1u);
;         const unsigned gen = old / nloc;
;         if (old + 1u == (gen + 1u) * nloc) {
;             __builtin_amdgcn_fence(__ATOMIC_RELEASE, "agent");
;             asm volatile("s_waitcnt vmcnt(0)" ::: "memory");
;             const unsigned og = xb_add(&bar[XB_TOP], 1u);
;             const unsigned tg = og / nx;
;             asm volatile("buffer_inv sc1" ::: "memory");
;             if (og + 1u == (tg + 1u) * nx) xb_add(&bar[XB_TOPGEN], 1u);
;             else XB_SPIN(xb_ld(&bar[XB_TOPGEN]) == tg, bar);
.LBB0_495:
	s_or_b64 exec, exec, s[20:21]
	v_cvt_f32_u32_e32 v3, v1
	s_waitcnt vmcnt(0)
	v_readfirstlane_b32 s12, v2
	buffer_inv sc1
	s_add_u32 s20, s58, 0xc93b500
	v_rcp_iflag_f32_e32 v3, v3
	v_add_u32_e32 v0, s12, v0
	s_addc_u32 s21, s59, 0
	s_mov_b64 s[22:23], -1
	v_mul_f32_e32 v2, 0x4f7ffffe, v3
	v_cvt_u32_f32_e32 v2, v2
	v_sub_u32_e32 v3, 0, v1
	v_mul_lo_u32 v3, v3, v2
	v_mul_hi_u32 v3, v2, v3
	v_add_u32_e32 v2, v2, v3
	v_mul_hi_u32 v2, v0, v2
	v_mul_lo_u32 v3, v2, v1
	v_sub_u32_e32 v3, v0, v3
	v_add_u32_e32 v4, 1, v2
	v_cmp_ge_u32_e32 vcc, v3, v1
	v_add_u32_e32 v0, 1, v0
	s_nop 0
	v_cndmask_b32_e32 v2, v2, v4, vcc
	v_sub_u32_e32 v4, v3, v1
	v_cndmask_b32_e32 v3, v3, v4, vcc
	v_add_u32_e32 v4, 1, v2
	v_cmp_ge_u32_e32 vcc, v3, v1
	s_nop 1
	v_cndmask_b32_e32 v2, v2, v4, vcc
	v_mul_lo_u32 v3, v1, v2
	v_add_u32_e32 v1, v3, v1
	v_cmp_ne_u32_e32 vcc, v0, v1
	v_mov_b64_e32 v[0:1], s[20:21]
	v_mov_b32_e32 v30, 0
	s_and_saveexec_b64 s[18:19], vcc
	s_cbranch_execz .LBB0_507
	v_mov_b32_e32 v30, 1
	v_mov_b32_e32 v0, 0
	global_load_dword v1, v0, s[20:21] sc1
	s_mov_b64 s[44:45], 0
	s_waitcnt vmcnt(0)
	v_cmp_eq_u32_e32 vcc, v1, v2
	s_and_saveexec_b64 s[24:25], vcc
	s_cbranch_execz .LBB0_506
	s_add_u32 s22, s58, 0xc938200
	s_addc_u32 s23, s59, 0
	s_mov_b32 s12, 1
	s_branch .LBB0_499

; __device__ __forceinline__ unsigned xb_ld(unsigned* p)              { return __hip_atomic_load(p, __ATOMIC_RELAXED, __HIP_MEMORY_SCOPE_AGENT); }
; __device__ __forceinline__ unsigned xb_add(unsigned* p, unsigned v) { return __hip_atomic_fetch_add(p, v, __ATOMIC_RELAXED, __HIP_MEMORY_SCOPE_AGENT); }
; #define XB_SPIN(cond, bar) do { unsigned _sp = 0; while (cond) { __builtin_amdgcn_s_sleep(1); \
;     if ((++_sp & 255u) == 0u) { if (xb_ld(&(bar)[XB_TMO])) break; if (_sp > XB_SPIN_CAP) { atomicAdd(&(bar)[XB_TMO], 1u); break; } } } } while (0)
; __device__ __forceinline__ void xcd_barrier(const XcdBarrier& b) {
;     ...
;             if (og + 1u == (tg + 1u) * nx) xb_add(&bar[XB_TOPGEN], 1u);
;             else XB_SPIN(xb_ld(&bar[XB_TOPGEN]) == tg, bar);
;             xb_add(&bar[XB_XGEN(b.x)], 1u);
;             asm volatile("s_waitcnt vmcnt(0)" ::: "memory");
.LBB0_509:
	s_or_b64 exec, exec, s[18:19]
	v_cmp_eq_u32_e32 vcc, 0, v30
	s_and_saveexec_b64 s[18:19], vcc
	s_cbranch_execz .LBB0_511
	s_mov_b64 exec, 0xffff
	v_mbcnt_lo_u32_b32 v0, -1, 0
	v_lshlrev_b32_e32 v0, 8, v0
	v_mov_b32_e32 v1, 1
	s_add_u32 s20, s58, 0xc93a400
	s_addc_u32 s21, s59, 0
	global_atomic_add v0, v1, s[20:21]
	s_mov_b64 exec, 1

; __device__ __forceinline__ unsigned xb_ld(unsigned* p)              { return __hip_atomic_load(p, __ATOMIC_RELAXED, __HIP_MEMORY_SCOPE_AGENT); }
; __device__ __forceinline__ unsigned xb_add(unsigned* p, unsigned v) { return __hip_atomic_fetch_add(p, v, __ATOMIC_RELAXED, __HIP_MEMORY_SCOPE_AGENT); }
; #define XB_SPIN(cond, bar) do { unsigned _sp = 0; while (cond) { __builtin_amdgcn_s_sleep(1); \
;     if ((++_sp & 255u) == 0u) { if (xb_ld(&(bar)[XB_TMO])) break; if (_sp > XB_SPIN_CAP) { atomicAdd(&(bar)[XB_TMO], 1u); break; } } } } while (0)
; __device__ __forceinline__ void xcd_barrier(const XcdBarrier& b) {
;     ...
;         const unsigned old = xb_add(&bar[XB_XSUB(b.x)], 1u);
;         const unsigned gen = old / nloc;
;         if (old + 1u == (gen + 1u) * nloc) {
;             __builtin_amdgcn_fence(__ATOMIC_RELEASE, "agent");
;             asm volatile("s_waitcnt vmcnt(0)" ::: "memory");
;             const unsigned og = xb_add(&bar[XB_TOP], 1u);
;             const unsigned tg = og / nx;
;             asm volatile("buffer_inv sc1" ::: "memory");
;             if (og + 1u == (tg + 1u) * nx) xb_add(&bar[XB_TOPGEN], 1u);
;             else XB_SPIN(xb_ld(&bar[XB_TOPGEN]) == tg, bar);
.LBB0_616:
	s_or_b64 exec, exec, s[8:9]
	v_cvt_f32_u32_e32 v3, v1
	s_waitcnt vmcnt(0)
	v_readfirstlane_b32 s6, v2
	buffer_inv sc1
	s_add_u32 s8, s58, 0xc93b500
	v_rcp_iflag_f32_e32 v3, v3
	v_add_u32_e32 v0, s6, v0
	s_addc_u32 s9, s59, 0
	s_mov_b64 s[20:21], -1
	v_mul_f32_e32 v2, 0x4f7ffffe, v3
	v_cvt_u32_f32_e32 v2, v2
	v_sub_u32_e32 v3, 0, v1
	v_mul_lo_u32 v3, v3, v2
	v_mul_hi_u32 v3, v2, v3
	v_add_u32_e32 v2, v2, v3
	v_mul_hi_u32 v2, v0, v2
	v_mul_lo_u32 v3, v2, v1
	v_sub_u32_e32 v3, v0, v3
	v_add_u32_e32 v4, 1, v2
	v_cmp_ge_u32_e32 vcc, v3, v1
	v_add_u32_e32 v0, 1, v0
	s_nop 0
	v_cndmask_b32_e32 v2, v2, v4, vcc
	v_sub_u32_e32 v4, v3, v1
	v_cndmask_b32_e32 v3, v3, v4, vcc
	v_add_u32_e32 v4, 1, v2
	v_cmp_ge_u32_e32 vcc, v3, v1
	s_nop 1
	v_cndmask_b32_e32 v2, v2, v4, vcc
	v_mul_lo_u32 v3, v1, v2
	v_add_u32_e32 v1, v3, v1
	v_cmp_ne_u32_e32 vcc, v0, v1
	v_mov_b64_e32 v[0:1], s[8:9]
	v_mov_b32_e32 v30, 0
	s_and_saveexec_b64 s[6:7], vcc
	s_cbranch_execz .LBB0_628
	v_mov_b32_e32 v30, 1
	v_mov_b32_e32 v0, 0
	global_load_dword v1, v0, s[8:9] sc1
	s_mov_b64 s[36:37], 0
	s_waitcnt vmcnt(0)
	v_cmp_eq_u32_e32 vcc, v1, v2
	s_and_saveexec_b64 s[24:25], vcc
	s_cbranch_execz .LBB0_627
	s_add_u32 s20, s58, 0xc938200
	s_addc_u32 s21, s59, 0
	s_mov_b32 s12, 1
	s_branch .LBB0_620

; __device__ __forceinline__ unsigned xb_ld(unsigned* p)              { return __hip_atomic_load(p, __ATOMIC_RELAXED, __HIP_MEMORY_SCOPE_AGENT); }
; __device__ __forceinline__ unsigned xb_add(unsigned* p, unsigned v) { return __hip_atomic_fetch_add(p, v, __ATOMIC_RELAXED, __HIP_MEMORY_SCOPE_AGENT); }
; #define XB_SPIN(cond, bar) do { unsigned _sp = 0; while (cond) { __builtin_amdgcn_s_sleep(1); \
;     if ((++_sp & 255u) == 0u) { if (xb_ld(&(bar)[XB_TMO])) break; if (_sp > XB_SPIN_CAP) { atomicAdd(&(bar)[XB_TMO], 1u); break; } } } } while (0)
; __device__ __forceinline__ void xcd_barrier(const XcdBarrier& b) {
;     ...
;         const unsigned old = xb_add(&bar[XB_XSUB(b.x)], 1u);
;         const unsigned gen = old / nloc;
;         if (old + 1u == (gen + 1u) * nloc) {
;             __builtin_amdgcn_fence(__ATOMIC_RELEASE, "agent");
;             asm volatile("s_waitcnt vmcnt(0)" ::: "memory");
;             const unsigned og = xb_add(&bar[XB_TOP], 1u);
;             const unsigned tg = og / nx;
;             asm volatile("buffer_inv sc1" ::: "memory");
;             if (og + 1u == (tg + 1u) * nx) xb_add(&bar[XB_TOPGEN], 1u);
;             else XB_SPIN(xb_ld(&bar[XB_TOPGEN]) == tg, bar);
.LBB0_730:
	s_or_b64 exec, exec, s[12:13]
	v_cvt_f32_u32_e32 v3, v1
	s_waitcnt vmcnt(0)
	v_readfirstlane_b32 s3, v2
	buffer_inv sc1
	s_add_u32 s12, s58, 0xc93b500
	v_rcp_iflag_f32_e32 v3, v3
	v_add_u32_e32 v0, s3, v0
	s_addc_u32 s13, s59, 0
	s_mov_b64 s[14:15], -1
	v_mul_f32_e32 v2, 0x4f7ffffe, v3
	v_cvt_u32_f32_e32 v2, v2
	v_sub_u32_e32 v3, 0, v1
	v_mul_lo_u32 v3, v3, v2
	v_mul_hi_u32 v3, v2, v3
	v_add_u32_e32 v2, v2, v3
	v_mul_hi_u32 v2, v0, v2
	v_mul_lo_u32 v3, v2, v1
	v_sub_u32_e32 v3, v0, v3
	v_add_u32_e32 v4, 1, v2
	v_cmp_ge_u32_e32 vcc, v3, v1
	v_add_u32_e32 v0, 1, v0
	s_nop 0
	v_cndmask_b32_e32 v2, v2, v4, vcc
	v_sub_u32_e32 v4, v3, v1
	v_cndmask_b32_e32 v3, v3, v4, vcc
	v_add_u32_e32 v4, 1, v2
	v_cmp_ge_u32_e32 vcc, v3, v1
	s_nop 1
	v_cndmask_b32_e32 v2, v2, v4, vcc
	v_mul_lo_u32 v3, v1, v2
	v_add_u32_e32 v1, v3, v1
	v_cmp_ne_u32_e32 vcc, v0, v1
	v_mov_b64_e32 v[0:1], s[12:13]
	v_mov_b32_e32 v30, 0
	s_and_saveexec_b64 s[8:9], vcc
	s_cbranch_execz .LBB0_742
	v_mov_b32_e32 v30, 1
	v_mov_b32_e32 v0, 0
	global_load_dword v1, v0, s[12:13] sc1
	s_mov_b64 s[24:25], 0
	s_waitcnt vmcnt(0)
	v_cmp_eq_u32_e32 vcc, v1, v2
	s_and_saveexec_b64 s[22:23], vcc
	s_cbranch_execz .LBB0_741
	s_add_u32 s14, s58, 0xc938200
	s_addc_u32 s15, s59, 0
	s_mov_b32 s3, 1
	s_branch .LBB0_734

; __device__ __forceinline__ unsigned xb_ld(unsigned* p)              { return __hip_atomic_load(p, __ATOMIC_RELAXED, __HIP_MEMORY_SCOPE_AGENT); }
; __device__ __forceinline__ unsigned xb_add(unsigned* p, unsigned v) { return __hip_atomic_fetch_add(p, v, __ATOMIC_RELAXED, __HIP_MEMORY_SCOPE_AGENT); }
; #define XB_SPIN(cond, bar) do { unsigned _sp = 0; while (cond) { __builtin_amdgcn_s_sleep(1); \
;     if ((++_sp & 255u) == 0u) { if (xb_ld(&(bar)[XB_TMO])) break; if (_sp > XB_SPIN_CAP) { atomicAdd(&(bar)[XB_TMO], 1u); break; } } } } while (0)
; __device__ __forceinline__ void xcd_barrier(const XcdBarrier& b) {
;     ...
;             if (og + 1u == (tg + 1u) * nx) xb_add(&bar[XB_TOPGEN], 1u);
;             else XB_SPIN(xb_ld(&bar[XB_TOPGEN]) == tg, bar);
;             xb_add(&bar[XB_XGEN(b.x)], 1u);
;             asm volatile("s_waitcnt vmcnt(0)" ::: "memory");
.LBB0_744:
	s_or_b64 exec, exec, s[8:9]
	v_cmp_eq_u32_e32 vcc, 0, v30
	s_and_saveexec_b64 s[8:9], vcc
	s_cbranch_execz .LBB0_746
	s_mov_b64 exec, 0xffff
	v_mbcnt_lo_u32_b32 v0, -1, 0
	v_lshlrev_b32_e32 v0, 8, v0
	v_mov_b32_e32 v1, 1
	s_add_u32 s12, s58, 0xc93a400
	s_addc_u32 s13, s59, 0
	global_atomic_add v0, v1, s[12:13]
	s_mov_b64 exec, 1
